# prep_even conv as one 16-token pass in x-row-major order (independent packed FMAs, no pads), interleaved DPP sums
# speedup vs baseline: 1.0341x; 1.0341x over previous
.LBB0_618:
	v_lshl_add_u32 v203, v178, 10, v179
	v_lshl_add_u32 v204, v178, 11, v180
	v_lshl_add_u32 v205, v178, 4, s3
	v_add_u32_e32 v204, 0xf800, v204
	s_waitcnt lgkmcnt(0)
	ds_read2st64_b32 v[104:105], v203 offset0:0 offset1:4
	ds_read2st64_b32 v[106:107], v203 offset0:8 offset1:12
	ds_read2st64_b32 v[108:109], v203 offset0:16 offset1:20
	ds_read2st64_b32 v[110:111], v203 offset0:24 offset1:28
	ds_read2st64_b32 v[112:113], v203 offset0:32 offset1:36
	ds_read2st64_b32 v[114:115], v203 offset0:40 offset1:44
	ds_read2st64_b32 v[116:117], v203 offset0:48 offset1:52
	ds_read2st64_b32 v[118:119], v203 offset0:56 offset1:60
	s_waitcnt lgkmcnt(7)
	ds_read2st64_b32 v[120:121], v203 offset0:64 offset1:68
	v_lshlrev_b32_e32 v150, 16, v104
	v_and_b32_e32 v151, 0xffff0000, v104
	v_pk_fma_f32 v[208:209], v[76:77], v[150:151], v[78:79]
	v_lshlrev_b32_e32 v152, 16, v105
	v_and_b32_e32 v153, 0xffff0000, v105
	v_pk_fma_f32 v[208:209], v[34:35], v[152:153], v[208:209]
	s_waitcnt lgkmcnt(7)
	ds_read2st64_b32 v[122:123], v203 offset0:72 offset1:76
	v_lshlrev_b32_e32 v154, 16, v106
	v_and_b32_e32 v155, 0xffff0000, v106
	v_pk_fma_f32 v[210:211], v[76:77], v[152:153], v[78:79]
	v_pk_fma_f32 v[208:209], v[92:93], v[154:155], v[208:209]
	v_pk_fma_f32 v[210:211], v[34:35], v[154:155], v[210:211]
	v_lshlrev_b32_e32 v150, 16, v107
	v_and_b32_e32 v151, 0xffff0000, v107
	v_pk_fma_f32 v[212:213], v[76:77], v[154:155], v[78:79]
	v_pk_fma_f32 v[208:209], v[52:53], v[150:151], v[208:209]
	v_pk_fma_f32 v[210:211], v[92:93], v[150:151], v[210:211]
	s_waitcnt lgkmcnt(7)
	ds_read2st64_b32 v[124:125], v203 offset0:80 offset1:84
	v_lshlrev_b32_e32 v152, 16, v108
	v_and_b32_e32 v153, 0xffff0000, v108
	v_pk_fma_f32 v[212:213], v[34:35], v[150:151], v[212:213]
	v_pk_fma_f32 v[214:215], v[76:77], v[150:151], v[78:79]
	v_pk_fma_f32 v[208:209], v[36:37], v[152:153], v[208:209]
	v_pk_fma_f32 v[210:211], v[52:53], v[152:153], v[210:211]
	v_pk_fma_f32 v[212:213], v[92:93], v[152:153], v[212:213]
	v_lshlrev_b32_e32 v154, 16, v109
	v_and_b32_e32 v155, 0xffff0000, v109
	v_pk_fma_f32 v[214:215], v[34:35], v[152:153], v[214:215]
	v_pk_fma_f32 v[216:217], v[76:77], v[152:153], v[78:79]
	v_pk_fma_f32 v[208:209], v[38:39], v[154:155], v[208:209]
	v_pk_fma_f32 v[210:211], v[36:37], v[154:155], v[210:211]
	v_pk_fma_f32 v[212:213], v[52:53], v[154:155], v[212:213]
	s_waitcnt lgkmcnt(7)
	ds_read2st64_b32 v[126:127], v203 offset0:88 offset1:92
	v_lshlrev_b32_e32 v150, 16, v110
	v_and_b32_e32 v151, 0xffff0000, v110
	v_pk_fma_f32 v[214:215], v[92:93], v[154:155], v[214:215]
	v_pk_fma_f32 v[216:217], v[34:35], v[154:155], v[216:217]
	v_pk_fma_f32 v[218:219], v[76:77], v[154:155], v[78:79]
	v_pk_fma_f32 v[208:209], v[40:41], v[150:151], v[208:209]
	v_pk_fma_f32 v[210:211], v[38:39], v[150:151], v[210:211]
	v_pk_fma_f32 v[212:213], v[36:37], v[150:151], v[212:213]
	v_pk_fma_f32 v[214:215], v[52:53], v[150:151], v[214:215]
	v_lshlrev_b32_e32 v152, 16, v111
	v_and_b32_e32 v153, 0xffff0000, v111
	v_pk_fma_f32 v[216:217], v[92:93], v[150:151], v[216:217]
	v_pk_fma_f32 v[218:219], v[34:35], v[150:151], v[218:219]
	v_pk_fma_f32 v[220:221], v[76:77], v[150:151], v[78:79]
	v_pk_fma_f32 v[208:209], v[54:55], v[152:153], v[208:209]
	v_pk_fma_f32 v[210:211], v[40:41], v[152:153], v[210:211]
	v_pk_fma_f32 v[212:213], v[38:39], v[152:153], v[212:213]
	v_pk_fma_f32 v[214:215], v[36:37], v[152:153], v[214:215]
	s_waitcnt lgkmcnt(7)
	ds_read2st64_b32 v[128:129], v203 offset0:96 offset1:100
	v_lshlrev_b32_e32 v154, 16, v112
	v_and_b32_e32 v155, 0xffff0000, v112
	v_pk_fma_f32 v[216:217], v[52:53], v[152:153], v[216:217]
	v_pk_fma_f32 v[218:219], v[92:93], v[152:153], v[218:219]
	v_pk_fma_f32 v[220:221], v[34:35], v[152:153], v[220:221]
	v_pk_fma_f32 v[222:223], v[76:77], v[152:153], v[78:79]
	v_pk_fma_f32 v[208:209], v[42:43], v[154:155], v[208:209]
	v_pk_fma_f32 v[210:211], v[54:55], v[154:155], v[210:211]
	v_pk_fma_f32 v[212:213], v[40:41], v[154:155], v[212:213]
	v_pk_fma_f32 v[214:215], v[38:39], v[154:155], v[214:215]
	v_pk_fma_f32 v[216:217], v[36:37], v[154:155], v[216:217]
	v_lshlrev_b32_e32 v150, 16, v113
	v_and_b32_e32 v151, 0xffff0000, v113
	v_pk_fma_f32 v[218:219], v[52:53], v[154:155], v[218:219]
	v_pk_fma_f32 v[220:221], v[92:93], v[154:155], v[220:221]
	v_pk_fma_f32 v[222:223], v[34:35], v[154:155], v[222:223]
	v_pk_fma_f32 v[224:225], v[76:77], v[154:155], v[78:79]
	v_pk_fma_f32 v[208:209], v[44:45], v[150:151], v[208:209]
	v_pk_fma_f32 v[210:211], v[42:43], v[150:151], v[210:211]
	v_pk_fma_f32 v[212:213], v[54:55], v[150:151], v[212:213]
	v_pk_fma_f32 v[214:215], v[40:41], v[150:151], v[214:215]
	v_pk_fma_f32 v[216:217], v[38:39], v[150:151], v[216:217]
	s_waitcnt lgkmcnt(7)
	ds_read2st64_b32 v[130:131], v203 offset0:104 offset1:108
	v_lshlrev_b32_e32 v152, 16, v114
	v_and_b32_e32 v153, 0xffff0000, v114
	v_pk_fma_f32 v[218:219], v[36:37], v[150:151], v[218:219]
	v_pk_fma_f32 v[220:221], v[52:53], v[150:151], v[220:221]
	v_pk_fma_f32 v[222:223], v[92:93], v[150:151], v[222:223]
	v_pk_fma_f32 v[224:225], v[34:35], v[150:151], v[224:225]
	v_pk_fma_f32 v[226:227], v[76:77], v[150:151], v[78:79]
	v_pk_fma_f32 v[208:209], v[46:47], v[152:153], v[208:209]
	v_pk_fma_f32 v[210:211], v[44:45], v[152:153], v[210:211]
	v_pk_fma_f32 v[212:213], v[42:43], v[152:153], v[212:213]
	v_pk_fma_f32 v[214:215], v[54:55], v[152:153], v[214:215]
	v_pk_fma_f32 v[216:217], v[40:41], v[152:153], v[216:217]
	v_pk_fma_f32 v[218:219], v[38:39], v[152:153], v[218:219]
	v_lshlrev_b32_e32 v154, 16, v115
	v_and_b32_e32 v155, 0xffff0000, v115
	v_pk_fma_f32 v[220:221], v[36:37], v[152:153], v[220:221]
	v_pk_fma_f32 v[222:223], v[52:53], v[152:153], v[222:223]
	v_pk_fma_f32 v[224:225], v[92:93], v[152:153], v[224:225]
	v_pk_fma_f32 v[226:227], v[34:35], v[152:153], v[226:227]
	v_pk_fma_f32 v[228:229], v[76:77], v[152:153], v[78:79]
	v_pk_fma_f32 v[208:209], v[56:57], v[154:155], v[208:209]
	v_pk_fma_f32 v[210:211], v[46:47], v[154:155], v[210:211]
	v_pk_fma_f32 v[212:213], v[44:45], v[154:155], v[212:213]
	v_pk_fma_f32 v[214:215], v[42:43], v[154:155], v[214:215]
	v_pk_fma_f32 v[216:217], v[54:55], v[154:155], v[216:217]
	v_pk_fma_f32 v[218:219], v[40:41], v[154:155], v[218:219]
	s_waitcnt lgkmcnt(7)
	ds_read2st64_b32 v[132:133], v203 offset0:112 offset1:116
	v_lshlrev_b32_e32 v150, 16, v116
	v_and_b32_e32 v151, 0xffff0000, v116
	v_pk_fma_f32 v[220:221], v[38:39], v[154:155], v[220:221]
	v_pk_fma_f32 v[222:223], v[36:37], v[154:155], v[222:223]
	v_pk_fma_f32 v[224:225], v[52:53], v[154:155], v[224:225]
	v_pk_fma_f32 v[226:227], v[92:93], v[154:155], v[226:227]
	v_pk_fma_f32 v[228:229], v[34:35], v[154:155], v[228:229]
	v_pk_fma_f32 v[230:231], v[76:77], v[154:155], v[78:79]
	v_pk_fma_f32 v[208:209], v[48:49], v[150:151], v[208:209]
	v_pk_fma_f32 v[210:211], v[56:57], v[150:151], v[210:211]
	v_pk_fma_f32 v[212:213], v[46:47], v[150:151], v[212:213]
	v_pk_fma_f32 v[214:215], v[44:45], v[150:151], v[214:215]
	v_pk_fma_f32 v[216:217], v[42:43], v[150:151], v[216:217]
	v_pk_fma_f32 v[218:219], v[54:55], v[150:151], v[218:219]
	v_pk_fma_f32 v[220:221], v[40:41], v[150:151], v[220:221]
	v_lshlrev_b32_e32 v152, 16, v117
	v_and_b32_e32 v153, 0xffff0000, v117
	v_pk_fma_f32 v[222:223], v[38:39], v[150:151], v[222:223]
	v_pk_fma_f32 v[224:225], v[36:37], v[150:151], v[224:225]
	v_pk_fma_f32 v[226:227], v[52:53], v[150:151], v[226:227]
	v_pk_fma_f32 v[228:229], v[92:93], v[150:151], v[228:229]
	v_pk_fma_f32 v[230:231], v[34:35], v[150:151], v[230:231]
	v_pk_fma_f32 v[232:233], v[76:77], v[150:151], v[78:79]
	v_pk_fma_f32 v[208:209], v[50:51], v[152:153], v[208:209]
	v_pk_fma_f32 v[210:211], v[48:49], v[152:153], v[210:211]
	v_pk_fma_f32 v[212:213], v[56:57], v[152:153], v[212:213]
	v_pk_fma_f32 v[214:215], v[46:47], v[152:153], v[214:215]
	v_pk_fma_f32 v[216:217], v[44:45], v[152:153], v[216:217]
	v_pk_fma_f32 v[218:219], v[42:43], v[152:153], v[218:219]
	v_pk_fma_f32 v[220:221], v[54:55], v[152:153], v[220:221]
	s_waitcnt lgkmcnt(7)
	ds_read2st64_b32 v[134:135], v203 offset0:120 offset1:124
	v_lshlrev_b32_e32 v154, 16, v118
	v_and_b32_e32 v155, 0xffff0000, v118
	v_pk_fma_f32 v[222:223], v[40:41], v[152:153], v[222:223]
	v_pk_fma_f32 v[224:225], v[38:39], v[152:153], v[224:225]
	v_pk_fma_f32 v[226:227], v[36:37], v[152:153], v[226:227]
	v_pk_fma_f32 v[228:229], v[52:53], v[152:153], v[228:229]
	v_pk_fma_f32 v[230:231], v[92:93], v[152:153], v[230:231]
	v_pk_fma_f32 v[232:233], v[34:35], v[152:153], v[232:233]
	v_pk_fma_f32 v[234:235], v[76:77], v[152:153], v[78:79]
	v_pk_fma_f32 v[208:209], v[60:61], v[154:155], v[208:209]
	v_pk_fma_f32 v[210:211], v[50:51], v[154:155], v[210:211]
	v_pk_fma_f32 v[212:213], v[48:49], v[154:155], v[212:213]
	v_pk_fma_f32 v[214:215], v[56:57], v[154:155], v[214:215]
	v_pk_fma_f32 v[216:217], v[46:47], v[154:155], v[216:217]
	v_pk_fma_f32 v[218:219], v[44:45], v[154:155], v[218:219]
	v_pk_fma_f32 v[220:221], v[42:43], v[154:155], v[220:221]
	v_pk_fma_f32 v[222:223], v[54:55], v[154:155], v[222:223]
	v_lshlrev_b32_e32 v150, 16, v119
	v_and_b32_e32 v151, 0xffff0000, v119
	v_pk_fma_f32 v[224:225], v[40:41], v[154:155], v[224:225]
	v_pk_fma_f32 v[226:227], v[38:39], v[154:155], v[226:227]
	v_pk_fma_f32 v[228:229], v[36:37], v[154:155], v[228:229]
	v_pk_fma_f32 v[230:231], v[52:53], v[154:155], v[230:231]
	v_pk_fma_f32 v[232:233], v[92:93], v[154:155], v[232:233]
	v_pk_fma_f32 v[234:235], v[34:35], v[154:155], v[234:235]
	v_pk_fma_f32 v[236:237], v[76:77], v[154:155], v[78:79]
	v_pk_fma_f32 v[208:209], v[58:59], v[150:151], v[208:209]
	v_pk_fma_f32 v[210:211], v[60:61], v[150:151], v[210:211]
	v_pk_fma_f32 v[212:213], v[50:51], v[150:151], v[212:213]
	v_pk_fma_f32 v[214:215], v[48:49], v[150:151], v[214:215]
	v_pk_fma_f32 v[216:217], v[56:57], v[150:151], v[216:217]
	v_pk_fma_f32 v[218:219], v[46:47], v[150:151], v[218:219]
	v_pk_fma_f32 v[220:221], v[44:45], v[150:151], v[220:221]
	v_pk_fma_f32 v[222:223], v[42:43], v[150:151], v[222:223]
	s_waitcnt lgkmcnt(7)
	ds_read2st64_b32 v[136:137], v203 offset0:128 offset1:132
	v_lshlrev_b32_e32 v152, 16, v120
	v_and_b32_e32 v153, 0xffff0000, v120
	v_pk_fma_f32 v[224:225], v[54:55], v[150:151], v[224:225]
	v_pk_fma_f32 v[226:227], v[40:41], v[150:151], v[226:227]
	v_pk_fma_f32 v[228:229], v[38:39], v[150:151], v[228:229]
	v_pk_fma_f32 v[230:231], v[36:37], v[150:151], v[230:231]
	v_pk_fma_f32 v[232:233], v[52:53], v[150:151], v[232:233]
	v_pk_fma_f32 v[234:235], v[92:93], v[150:151], v[234:235]
	v_pk_fma_f32 v[236:237], v[34:35], v[150:151], v[236:237]
	v_pk_fma_f32 v[238:239], v[76:77], v[150:151], v[78:79]
	v_pk_fma_f32 v[208:209], v[62:63], v[152:153], v[208:209]
	v_pk_fma_f32 v[210:211], v[58:59], v[152:153], v[210:211]
	v_pk_fma_f32 v[212:213], v[60:61], v[152:153], v[212:213]
	v_pk_fma_f32 v[214:215], v[50:51], v[152:153], v[214:215]
	v_pk_fma_f32 v[216:217], v[48:49], v[152:153], v[216:217]
	v_pk_fma_f32 v[218:219], v[56:57], v[152:153], v[218:219]
	v_pk_fma_f32 v[220:221], v[46:47], v[152:153], v[220:221]
	v_pk_fma_f32 v[222:223], v[44:45], v[152:153], v[222:223]
	v_lshlrev_b32_e32 v154, 16, v121
	v_and_b32_e32 v155, 0xffff0000, v121
	v_pk_fma_f32 v[224:225], v[42:43], v[152:153], v[224:225]
	v_pk_fma_f32 v[226:227], v[54:55], v[152:153], v[226:227]
	v_pk_fma_f32 v[228:229], v[40:41], v[152:153], v[228:229]
	v_pk_fma_f32 v[230:231], v[38:39], v[152:153], v[230:231]
	v_pk_fma_f32 v[232:233], v[36:37], v[152:153], v[232:233]
	v_pk_fma_f32 v[234:235], v[52:53], v[152:153], v[234:235]
	v_pk_fma_f32 v[236:237], v[92:93], v[152:153], v[236:237]
	v_pk_fma_f32 v[238:239], v[34:35], v[152:153], v[238:239]
	v_pk_fma_f32 v[208:209], v[64:65], v[154:155], v[208:209]
	v_pk_fma_f32 v[210:211], v[62:63], v[154:155], v[210:211]
	v_pk_fma_f32 v[212:213], v[58:59], v[154:155], v[212:213]
	v_pk_fma_f32 v[214:215], v[60:61], v[154:155], v[214:215]
	v_pk_fma_f32 v[216:217], v[50:51], v[154:155], v[216:217]
	v_pk_fma_f32 v[218:219], v[48:49], v[154:155], v[218:219]
	v_pk_fma_f32 v[220:221], v[56:57], v[154:155], v[220:221]
	v_pk_fma_f32 v[222:223], v[46:47], v[154:155], v[222:223]
	s_waitcnt lgkmcnt(7)
	ds_read2st64_b32 v[138:139], v203 offset0:136 offset1:140
	v_lshlrev_b32_e32 v150, 16, v122
	v_and_b32_e32 v151, 0xffff0000, v122
	v_pk_fma_f32 v[224:225], v[44:45], v[154:155], v[224:225]
	v_pk_fma_f32 v[226:227], v[42:43], v[154:155], v[226:227]
	v_pk_fma_f32 v[228:229], v[54:55], v[154:155], v[228:229]
	v_pk_fma_f32 v[230:231], v[40:41], v[154:155], v[230:231]
	v_pk_fma_f32 v[232:233], v[38:39], v[154:155], v[232:233]
	v_pk_fma_f32 v[234:235], v[36:37], v[154:155], v[234:235]
	v_pk_fma_f32 v[236:237], v[52:53], v[154:155], v[236:237]
	v_pk_fma_f32 v[238:239], v[92:93], v[154:155], v[238:239]
	v_pk_fma_f32 v[208:209], v[66:67], v[150:151], v[208:209]
	v_pk_fma_f32 v[210:211], v[64:65], v[150:151], v[210:211]
	v_pk_fma_f32 v[212:213], v[62:63], v[150:151], v[212:213]
	v_pk_fma_f32 v[214:215], v[58:59], v[150:151], v[214:215]
	v_pk_fma_f32 v[216:217], v[60:61], v[150:151], v[216:217]
	v_pk_fma_f32 v[218:219], v[50:51], v[150:151], v[218:219]
	v_pk_fma_f32 v[220:221], v[48:49], v[150:151], v[220:221]
	v_pk_fma_f32 v[222:223], v[56:57], v[150:151], v[222:223]
	v_lshlrev_b32_e32 v152, 16, v123
	v_and_b32_e32 v153, 0xffff0000, v123
	v_pk_fma_f32 v[224:225], v[46:47], v[150:151], v[224:225]
	v_pk_fma_f32 v[226:227], v[44:45], v[150:151], v[226:227]
	v_pk_fma_f32 v[228:229], v[42:43], v[150:151], v[228:229]
	v_pk_fma_f32 v[230:231], v[54:55], v[150:151], v[230:231]
	v_pk_fma_f32 v[232:233], v[40:41], v[150:151], v[232:233]
	v_pk_fma_f32 v[234:235], v[38:39], v[150:151], v[234:235]
	v_pk_fma_f32 v[236:237], v[36:37], v[150:151], v[236:237]
	v_pk_fma_f32 v[238:239], v[52:53], v[150:151], v[238:239]
	v_pk_fma_f32 v[208:209], v[84:85], v[152:153], v[208:209]
	v_pk_fma_f32 v[210:211], v[66:67], v[152:153], v[210:211]
	v_pk_fma_f32 v[212:213], v[64:65], v[152:153], v[212:213]
	v_pk_fma_f32 v[214:215], v[62:63], v[152:153], v[214:215]
	v_pk_fma_f32 v[216:217], v[58:59], v[152:153], v[216:217]
	v_pk_fma_f32 v[218:219], v[60:61], v[152:153], v[218:219]
	v_pk_fma_f32 v[220:221], v[50:51], v[152:153], v[220:221]
	v_pk_fma_f32 v[222:223], v[48:49], v[152:153], v[222:223]
	s_waitcnt lgkmcnt(7)
	ds_read2st64_b32 v[140:141], v203 offset0:144 offset1:148
	v_lshlrev_b32_e32 v154, 16, v124
	v_and_b32_e32 v155, 0xffff0000, v124
	v_pk_fma_f32 v[224:225], v[56:57], v[152:153], v[224:225]
	v_pk_fma_f32 v[226:227], v[46:47], v[152:153], v[226:227]
	v_pk_fma_f32 v[228:229], v[44:45], v[152:153], v[228:229]
	v_pk_fma_f32 v[230:231], v[42:43], v[152:153], v[230:231]
	v_pk_fma_f32 v[232:233], v[54:55], v[152:153], v[232:233]
	v_pk_fma_f32 v[234:235], v[40:41], v[152:153], v[234:235]
	v_pk_fma_f32 v[236:237], v[38:39], v[152:153], v[236:237]
	v_pk_fma_f32 v[238:239], v[36:37], v[152:153], v[238:239]
	v_pk_fma_f32 v[208:209], v[68:69], v[154:155], v[208:209]
	v_pk_fma_f32 v[210:211], v[84:85], v[154:155], v[210:211]
	v_pk_fma_f32 v[212:213], v[66:67], v[154:155], v[212:213]
	v_pk_fma_f32 v[214:215], v[64:65], v[154:155], v[214:215]
	v_pk_fma_f32 v[216:217], v[62:63], v[154:155], v[216:217]
	v_pk_fma_f32 v[218:219], v[58:59], v[154:155], v[218:219]
	v_pk_fma_f32 v[220:221], v[60:61], v[154:155], v[220:221]
	v_pk_fma_f32 v[222:223], v[50:51], v[154:155], v[222:223]
	v_lshlrev_b32_e32 v150, 16, v125
	v_and_b32_e32 v151, 0xffff0000, v125
	v_pk_fma_f32 v[224:225], v[48:49], v[154:155], v[224:225]
	v_pk_fma_f32 v[226:227], v[56:57], v[154:155], v[226:227]
	v_pk_fma_f32 v[228:229], v[46:47], v[154:155], v[228:229]
	v_pk_fma_f32 v[230:231], v[44:45], v[154:155], v[230:231]
	v_pk_fma_f32 v[232:233], v[42:43], v[154:155], v[232:233]
	v_pk_fma_f32 v[234:235], v[54:55], v[154:155], v[234:235]
	v_pk_fma_f32 v[236:237], v[40:41], v[154:155], v[236:237]
	v_pk_fma_f32 v[238:239], v[38:39], v[154:155], v[238:239]
	v_pk_fma_f32 v[208:209], v[70:71], v[150:151], v[208:209]
	v_pk_fma_f32 v[210:211], v[68:69], v[150:151], v[210:211]
	v_pk_fma_f32 v[212:213], v[84:85], v[150:151], v[212:213]
	v_pk_fma_f32 v[214:215], v[66:67], v[150:151], v[214:215]
	v_pk_fma_f32 v[216:217], v[64:65], v[150:151], v[216:217]
	v_pk_fma_f32 v[218:219], v[62:63], v[150:151], v[218:219]
	v_pk_fma_f32 v[220:221], v[58:59], v[150:151], v[220:221]
	v_pk_fma_f32 v[222:223], v[60:61], v[150:151], v[222:223]
	s_waitcnt lgkmcnt(7)
	ds_read2st64_b32 v[142:143], v203 offset0:152 offset1:156
	v_lshlrev_b32_e32 v152, 16, v126
	v_and_b32_e32 v153, 0xffff0000, v126
	v_pk_fma_f32 v[224:225], v[50:51], v[150:151], v[224:225]
	v_pk_fma_f32 v[226:227], v[48:49], v[150:151], v[226:227]
	v_pk_fma_f32 v[228:229], v[56:57], v[150:151], v[228:229]
	v_pk_fma_f32 v[230:231], v[46:47], v[150:151], v[230:231]
	v_pk_fma_f32 v[232:233], v[44:45], v[150:151], v[232:233]
	v_pk_fma_f32 v[234:235], v[42:43], v[150:151], v[234:235]
	v_pk_fma_f32 v[236:237], v[54:55], v[150:151], v[236:237]
	v_pk_fma_f32 v[238:239], v[40:41], v[150:151], v[238:239]
	v_pk_fma_f32 v[208:209], v[72:73], v[152:153], v[208:209]
	v_pk_fma_f32 v[210:211], v[70:71], v[152:153], v[210:211]
	v_pk_fma_f32 v[212:213], v[68:69], v[152:153], v[212:213]
	v_pk_fma_f32 v[214:215], v[84:85], v[152:153], v[214:215]
	v_pk_fma_f32 v[216:217], v[66:67], v[152:153], v[216:217]
	v_pk_fma_f32 v[218:219], v[64:65], v[152:153], v[218:219]
	v_pk_fma_f32 v[220:221], v[62:63], v[152:153], v[220:221]
	v_pk_fma_f32 v[222:223], v[58:59], v[152:153], v[222:223]
	v_lshlrev_b32_e32 v154, 16, v127
	v_and_b32_e32 v155, 0xffff0000, v127
	v_pk_fma_f32 v[224:225], v[60:61], v[152:153], v[224:225]
	v_pk_fma_f32 v[226:227], v[50:51], v[152:153], v[226:227]
	v_pk_fma_f32 v[228:229], v[48:49], v[152:153], v[228:229]
	v_pk_fma_f32 v[230:231], v[56:57], v[152:153], v[230:231]
	v_pk_fma_f32 v[232:233], v[46:47], v[152:153], v[232:233]
	v_pk_fma_f32 v[234:235], v[44:45], v[152:153], v[234:235]
	v_pk_fma_f32 v[236:237], v[42:43], v[152:153], v[236:237]
	v_pk_fma_f32 v[238:239], v[54:55], v[152:153], v[238:239]
	v_pk_fma_f32 v[208:209], v[86:87], v[154:155], v[208:209]
	v_pk_fma_f32 v[210:211], v[72:73], v[154:155], v[210:211]
	v_pk_fma_f32 v[212:213], v[70:71], v[154:155], v[212:213]
	v_pk_fma_f32 v[214:215], v[68:69], v[154:155], v[214:215]
	v_pk_fma_f32 v[216:217], v[84:85], v[154:155], v[216:217]
	v_pk_fma_f32 v[218:219], v[66:67], v[154:155], v[218:219]
	v_pk_fma_f32 v[220:221], v[64:65], v[154:155], v[220:221]
	v_pk_fma_f32 v[222:223], v[62:63], v[154:155], v[222:223]
	s_waitcnt lgkmcnt(7)
	ds_read2st64_b32 v[144:145], v203 offset0:160 offset1:164
	v_lshlrev_b32_e32 v150, 16, v128
	v_and_b32_e32 v151, 0xffff0000, v128
	v_pk_fma_f32 v[224:225], v[58:59], v[154:155], v[224:225]
	v_pk_fma_f32 v[226:227], v[60:61], v[154:155], v[226:227]
	v_pk_fma_f32 v[228:229], v[50:51], v[154:155], v[228:229]
	v_pk_fma_f32 v[230:231], v[48:49], v[154:155], v[230:231]
	v_pk_fma_f32 v[232:233], v[56:57], v[154:155], v[232:233]
	v_pk_fma_f32 v[234:235], v[46:47], v[154:155], v[234:235]
	v_pk_fma_f32 v[236:237], v[44:45], v[154:155], v[236:237]
	v_pk_fma_f32 v[238:239], v[42:43], v[154:155], v[238:239]
	v_pk_fma_f32 v[208:209], v[74:75], v[150:151], v[208:209]
	v_pk_fma_f32 v[210:211], v[86:87], v[150:151], v[210:211]
	v_pk_fma_f32 v[212:213], v[72:73], v[150:151], v[212:213]
	v_pk_fma_f32 v[214:215], v[70:71], v[150:151], v[214:215]
	v_pk_fma_f32 v[216:217], v[68:69], v[150:151], v[216:217]
	v_pk_fma_f32 v[218:219], v[84:85], v[150:151], v[218:219]
	v_pk_fma_f32 v[220:221], v[66:67], v[150:151], v[220:221]
	v_pk_fma_f32 v[222:223], v[64:65], v[150:151], v[222:223]
	v_lshlrev_b32_e32 v152, 16, v129
	v_and_b32_e32 v153, 0xffff0000, v129
	v_pk_fma_f32 v[224:225], v[62:63], v[150:151], v[224:225]
	v_pk_fma_f32 v[226:227], v[58:59], v[150:151], v[226:227]
	v_pk_fma_f32 v[228:229], v[60:61], v[150:151], v[228:229]
	v_pk_fma_f32 v[230:231], v[50:51], v[150:151], v[230:231]
	v_pk_fma_f32 v[232:233], v[48:49], v[150:151], v[232:233]
	v_pk_fma_f32 v[234:235], v[56:57], v[150:151], v[234:235]
	v_pk_fma_f32 v[236:237], v[46:47], v[150:151], v[236:237]
	v_pk_fma_f32 v[238:239], v[44:45], v[150:151], v[238:239]
	v_pk_fma_f32 v[208:209], v[82:83], v[152:153], v[208:209]
	v_pk_fma_f32 v[210:211], v[74:75], v[152:153], v[210:211]
	v_pk_fma_f32 v[212:213], v[86:87], v[152:153], v[212:213]
	v_pk_fma_f32 v[214:215], v[72:73], v[152:153], v[214:215]
	v_pk_fma_f32 v[216:217], v[70:71], v[152:153], v[216:217]
	v_pk_fma_f32 v[218:219], v[68:69], v[152:153], v[218:219]
	v_pk_fma_f32 v[220:221], v[84:85], v[152:153], v[220:221]
	v_pk_fma_f32 v[222:223], v[66:67], v[152:153], v[222:223]
	s_waitcnt lgkmcnt(7)
	ds_read2st64_b32 v[146:147], v203 offset0:168 offset1:172
	v_lshlrev_b32_e32 v154, 16, v130
	v_and_b32_e32 v155, 0xffff0000, v130
	v_pk_fma_f32 v[224:225], v[64:65], v[152:153], v[224:225]
	v_pk_fma_f32 v[226:227], v[62:63], v[152:153], v[226:227]
	v_pk_fma_f32 v[228:229], v[58:59], v[152:153], v[228:229]
	v_pk_fma_f32 v[230:231], v[60:61], v[152:153], v[230:231]
	v_pk_fma_f32 v[232:233], v[50:51], v[152:153], v[232:233]
	v_pk_fma_f32 v[234:235], v[48:49], v[152:153], v[234:235]
	v_pk_fma_f32 v[236:237], v[56:57], v[152:153], v[236:237]
	v_pk_fma_f32 v[238:239], v[46:47], v[152:153], v[238:239]
	v_pk_fma_f32 v[208:209], v[88:89], v[154:155], v[208:209]
	v_pk_fma_f32 v[210:211], v[82:83], v[154:155], v[210:211]
	v_pk_fma_f32 v[212:213], v[74:75], v[154:155], v[212:213]
	v_pk_fma_f32 v[214:215], v[86:87], v[154:155], v[214:215]
	v_pk_fma_f32 v[216:217], v[72:73], v[154:155], v[216:217]
	v_pk_fma_f32 v[218:219], v[70:71], v[154:155], v[218:219]
	v_pk_fma_f32 v[220:221], v[68:69], v[154:155], v[220:221]
	v_pk_fma_f32 v[222:223], v[84:85], v[154:155], v[222:223]
	v_lshlrev_b32_e32 v150, 16, v131
	v_and_b32_e32 v151, 0xffff0000, v131
	v_pk_fma_f32 v[224:225], v[66:67], v[154:155], v[224:225]
	v_pk_fma_f32 v[226:227], v[64:65], v[154:155], v[226:227]
	v_pk_fma_f32 v[228:229], v[62:63], v[154:155], v[228:229]
	v_pk_fma_f32 v[230:231], v[58:59], v[154:155], v[230:231]
	v_pk_fma_f32 v[232:233], v[60:61], v[154:155], v[232:233]
	v_pk_fma_f32 v[234:235], v[50:51], v[154:155], v[234:235]
	v_pk_fma_f32 v[236:237], v[48:49], v[154:155], v[236:237]
	v_pk_fma_f32 v[238:239], v[56:57], v[154:155], v[238:239]
	v_pk_fma_f32 v[208:209], v[90:91], v[150:151], v[208:209]
	v_pk_fma_f32 v[210:211], v[88:89], v[150:151], v[210:211]
	v_pk_fma_f32 v[212:213], v[82:83], v[150:151], v[212:213]
	v_pk_fma_f32 v[214:215], v[74:75], v[150:151], v[214:215]
	v_pk_fma_f32 v[216:217], v[86:87], v[150:151], v[216:217]
	v_pk_fma_f32 v[218:219], v[72:73], v[150:151], v[218:219]
	v_pk_fma_f32 v[220:221], v[70:71], v[150:151], v[220:221]
	v_pk_fma_f32 v[222:223], v[68:69], v[150:151], v[222:223]
	s_waitcnt lgkmcnt(7)
	ds_read2st64_b32 v[148:149], v203 offset0:176 offset1:180
	v_lshlrev_b32_e32 v152, 16, v132
	v_and_b32_e32 v153, 0xffff0000, v132
	v_pk_fma_f32 v[224:225], v[84:85], v[150:151], v[224:225]
	v_pk_fma_f32 v[226:227], v[66:67], v[150:151], v[226:227]
	v_pk_fma_f32 v[228:229], v[64:65], v[150:151], v[228:229]
	v_pk_fma_f32 v[230:231], v[62:63], v[150:151], v[230:231]
	v_pk_fma_f32 v[232:233], v[58:59], v[150:151], v[232:233]
	v_pk_fma_f32 v[234:235], v[60:61], v[150:151], v[234:235]
	v_pk_fma_f32 v[236:237], v[50:51], v[150:151], v[236:237]
	v_pk_fma_f32 v[238:239], v[48:49], v[150:151], v[238:239]
	v_pk_fma_f32 v[208:209], v[94:95], v[152:153], v[208:209]
	v_pk_fma_f32 v[210:211], v[90:91], v[152:153], v[210:211]
	v_pk_fma_f32 v[212:213], v[88:89], v[152:153], v[212:213]
	v_pk_fma_f32 v[214:215], v[82:83], v[152:153], v[214:215]
	v_pk_fma_f32 v[216:217], v[74:75], v[152:153], v[216:217]
	v_pk_fma_f32 v[218:219], v[86:87], v[152:153], v[218:219]
	v_pk_fma_f32 v[220:221], v[72:73], v[152:153], v[220:221]
	v_pk_fma_f32 v[222:223], v[70:71], v[152:153], v[222:223]
	v_lshlrev_b32_e32 v154, 16, v133
	v_and_b32_e32 v155, 0xffff0000, v133
	v_pk_fma_f32 v[224:225], v[68:69], v[152:153], v[224:225]
	v_pk_fma_f32 v[226:227], v[84:85], v[152:153], v[226:227]
	v_pk_fma_f32 v[228:229], v[66:67], v[152:153], v[228:229]
	v_pk_fma_f32 v[230:231], v[64:65], v[152:153], v[230:231]
	v_pk_fma_f32 v[232:233], v[62:63], v[152:153], v[232:233]
	v_pk_fma_f32 v[234:235], v[58:59], v[152:153], v[234:235]
	v_pk_fma_f32 v[236:237], v[60:61], v[152:153], v[236:237]
	v_pk_fma_f32 v[238:239], v[50:51], v[152:153], v[238:239]
	v_pk_fma_f32 v[208:209], v[96:97], v[154:155], v[208:209]
	v_pk_fma_f32 v[210:211], v[94:95], v[154:155], v[210:211]
	v_pk_fma_f32 v[212:213], v[90:91], v[154:155], v[212:213]
	v_pk_fma_f32 v[214:215], v[88:89], v[154:155], v[214:215]
	v_pk_fma_f32 v[216:217], v[82:83], v[154:155], v[216:217]
	v_pk_fma_f32 v[218:219], v[74:75], v[154:155], v[218:219]
	v_pk_fma_f32 v[220:221], v[86:87], v[154:155], v[220:221]
	v_pk_fma_f32 v[222:223], v[72:73], v[154:155], v[222:223]
	s_waitcnt lgkmcnt(7)
	v_lshlrev_b32_e32 v150, 16, v134
	v_and_b32_e32 v151, 0xffff0000, v134
	v_pk_fma_f32 v[224:225], v[70:71], v[154:155], v[224:225]
	v_pk_fma_f32 v[226:227], v[68:69], v[154:155], v[226:227]
	v_pk_fma_f32 v[228:229], v[84:85], v[154:155], v[228:229]
	v_pk_fma_f32 v[230:231], v[66:67], v[154:155], v[230:231]
	v_pk_fma_f32 v[232:233], v[64:65], v[154:155], v[232:233]
	v_pk_fma_f32 v[234:235], v[62:63], v[154:155], v[234:235]
	v_pk_fma_f32 v[236:237], v[58:59], v[154:155], v[236:237]
	v_pk_fma_f32 v[238:239], v[60:61], v[154:155], v[238:239]
	v_pk_fma_f32 v[208:209], v[98:99], v[150:151], v[208:209]
	v_pk_fma_f32 v[210:211], v[96:97], v[150:151], v[210:211]
	v_pk_fma_f32 v[212:213], v[94:95], v[150:151], v[212:213]
	v_pk_fma_f32 v[214:215], v[90:91], v[150:151], v[214:215]
	v_pk_fma_f32 v[216:217], v[88:89], v[150:151], v[216:217]
	v_pk_fma_f32 v[218:219], v[82:83], v[150:151], v[218:219]
	v_pk_fma_f32 v[220:221], v[74:75], v[150:151], v[220:221]
	v_pk_fma_f32 v[222:223], v[86:87], v[150:151], v[222:223]
	v_lshlrev_b32_e32 v152, 16, v135
	v_and_b32_e32 v153, 0xffff0000, v135
	v_pk_fma_f32 v[224:225], v[72:73], v[150:151], v[224:225]
	v_pk_fma_f32 v[226:227], v[70:71], v[150:151], v[226:227]
	v_pk_fma_f32 v[228:229], v[68:69], v[150:151], v[228:229]
	v_pk_fma_f32 v[230:231], v[84:85], v[150:151], v[230:231]
	v_pk_fma_f32 v[232:233], v[66:67], v[150:151], v[232:233]
	v_pk_fma_f32 v[234:235], v[64:65], v[150:151], v[234:235]
	v_pk_fma_f32 v[236:237], v[62:63], v[150:151], v[236:237]
	v_pk_fma_f32 v[238:239], v[58:59], v[150:151], v[238:239]
	v_pk_fma_f32 v[210:211], v[98:99], v[152:153], v[210:211]
	v_pk_fma_f32 v[212:213], v[96:97], v[152:153], v[212:213]
	v_pk_fma_f32 v[214:215], v[94:95], v[152:153], v[214:215]
	v_pk_fma_f32 v[216:217], v[90:91], v[152:153], v[216:217]
	v_pk_fma_f32 v[218:219], v[88:89], v[152:153], v[218:219]
	v_pk_fma_f32 v[220:221], v[82:83], v[152:153], v[220:221]
	v_pk_fma_f32 v[222:223], v[74:75], v[152:153], v[222:223]
	v_pk_fma_f32 v[224:225], v[86:87], v[152:153], v[224:225]
	s_waitcnt lgkmcnt(6)
	v_lshlrev_b32_e32 v154, 16, v136
	v_and_b32_e32 v155, 0xffff0000, v136
	v_pk_fma_f32 v[226:227], v[72:73], v[152:153], v[226:227]
	v_pk_fma_f32 v[228:229], v[70:71], v[152:153], v[228:229]
	v_pk_fma_f32 v[230:231], v[68:69], v[152:153], v[230:231]
	v_pk_fma_f32 v[232:233], v[84:85], v[152:153], v[232:233]
	v_pk_fma_f32 v[234:235], v[66:67], v[152:153], v[234:235]
	v_pk_fma_f32 v[236:237], v[64:65], v[152:153], v[236:237]
	v_pk_fma_f32 v[238:239], v[62:63], v[152:153], v[238:239]
	v_pk_fma_f32 v[212:213], v[98:99], v[154:155], v[212:213]
	v_pk_fma_f32 v[214:215], v[96:97], v[154:155], v[214:215]
	v_pk_fma_f32 v[216:217], v[94:95], v[154:155], v[216:217]
	v_pk_fma_f32 v[218:219], v[90:91], v[154:155], v[218:219]
	v_pk_fma_f32 v[220:221], v[88:89], v[154:155], v[220:221]
	v_pk_fma_f32 v[222:223], v[82:83], v[154:155], v[222:223]
	v_pk_fma_f32 v[224:225], v[74:75], v[154:155], v[224:225]
	v_lshlrev_b32_e32 v150, 16, v137
	v_and_b32_e32 v151, 0xffff0000, v137
	v_pk_fma_f32 v[226:227], v[86:87], v[154:155], v[226:227]
	v_pk_fma_f32 v[228:229], v[72:73], v[154:155], v[228:229]
	v_pk_fma_f32 v[230:231], v[70:71], v[154:155], v[230:231]
	v_pk_fma_f32 v[232:233], v[68:69], v[154:155], v[232:233]
	v_pk_fma_f32 v[234:235], v[84:85], v[154:155], v[234:235]
	v_pk_fma_f32 v[236:237], v[66:67], v[154:155], v[236:237]
	v_pk_fma_f32 v[238:239], v[64:65], v[154:155], v[238:239]
	v_pk_fma_f32 v[214:215], v[98:99], v[150:151], v[214:215]
	v_pk_fma_f32 v[216:217], v[96:97], v[150:151], v[216:217]
	v_pk_fma_f32 v[218:219], v[94:95], v[150:151], v[218:219]
	v_pk_fma_f32 v[220:221], v[90:91], v[150:151], v[220:221]
	v_pk_fma_f32 v[222:223], v[88:89], v[150:151], v[222:223]
	v_pk_fma_f32 v[224:225], v[82:83], v[150:151], v[224:225]
	v_pk_fma_f32 v[226:227], v[74:75], v[150:151], v[226:227]
	s_waitcnt lgkmcnt(5)
	v_lshlrev_b32_e32 v152, 16, v138
	v_and_b32_e32 v153, 0xffff0000, v138
	v_pk_fma_f32 v[228:229], v[86:87], v[150:151], v[228:229]
	v_pk_fma_f32 v[230:231], v[72:73], v[150:151], v[230:231]
	v_pk_fma_f32 v[232:233], v[70:71], v[150:151], v[232:233]
	v_pk_fma_f32 v[234:235], v[68:69], v[150:151], v[234:235]
	v_pk_fma_f32 v[236:237], v[84:85], v[150:151], v[236:237]
	v_pk_fma_f32 v[238:239], v[66:67], v[150:151], v[238:239]
	v_pk_fma_f32 v[216:217], v[98:99], v[152:153], v[216:217]
	v_pk_fma_f32 v[218:219], v[96:97], v[152:153], v[218:219]
	v_pk_fma_f32 v[220:221], v[94:95], v[152:153], v[220:221]
	v_pk_fma_f32 v[222:223], v[90:91], v[152:153], v[222:223]
	v_pk_fma_f32 v[224:225], v[88:89], v[152:153], v[224:225]
	v_pk_fma_f32 v[226:227], v[82:83], v[152:153], v[226:227]
	v_lshlrev_b32_e32 v154, 16, v139
	v_and_b32_e32 v155, 0xffff0000, v139
	v_pk_fma_f32 v[228:229], v[74:75], v[152:153], v[228:229]
	v_pk_fma_f32 v[230:231], v[86:87], v[152:153], v[230:231]
	v_pk_fma_f32 v[232:233], v[72:73], v[152:153], v[232:233]
	v_pk_fma_f32 v[234:235], v[70:71], v[152:153], v[234:235]
	v_pk_fma_f32 v[236:237], v[68:69], v[152:153], v[236:237]
	v_pk_fma_f32 v[238:239], v[84:85], v[152:153], v[238:239]
	v_pk_fma_f32 v[218:219], v[98:99], v[154:155], v[218:219]
	v_pk_fma_f32 v[220:221], v[96:97], v[154:155], v[220:221]
	v_pk_fma_f32 v[222:223], v[94:95], v[154:155], v[222:223]
	v_pk_fma_f32 v[224:225], v[90:91], v[154:155], v[224:225]
	v_pk_fma_f32 v[226:227], v[88:89], v[154:155], v[226:227]
	v_pk_fma_f32 v[228:229], v[82:83], v[154:155], v[228:229]
	s_waitcnt lgkmcnt(4)
	v_lshlrev_b32_e32 v150, 16, v140
	v_and_b32_e32 v151, 0xffff0000, v140
	v_pk_fma_f32 v[230:231], v[74:75], v[154:155], v[230:231]
	v_pk_fma_f32 v[232:233], v[86:87], v[154:155], v[232:233]
	v_pk_fma_f32 v[234:235], v[72:73], v[154:155], v[234:235]
	v_pk_fma_f32 v[236:237], v[70:71], v[154:155], v[236:237]
	v_pk_fma_f32 v[238:239], v[68:69], v[154:155], v[238:239]
	v_pk_fma_f32 v[220:221], v[98:99], v[150:151], v[220:221]
	v_pk_fma_f32 v[222:223], v[96:97], v[150:151], v[222:223]
	v_pk_fma_f32 v[224:225], v[94:95], v[150:151], v[224:225]
	v_pk_fma_f32 v[226:227], v[90:91], v[150:151], v[226:227]
	v_pk_fma_f32 v[228:229], v[88:89], v[150:151], v[228:229]
	v_lshlrev_b32_e32 v152, 16, v141
	v_and_b32_e32 v153, 0xffff0000, v141
	v_pk_fma_f32 v[230:231], v[82:83], v[150:151], v[230:231]
	v_pk_fma_f32 v[232:233], v[74:75], v[150:151], v[232:233]
	v_pk_fma_f32 v[234:235], v[86:87], v[150:151], v[234:235]
	v_pk_fma_f32 v[236:237], v[72:73], v[150:151], v[236:237]
	v_pk_fma_f32 v[238:239], v[70:71], v[150:151], v[238:239]
	v_pk_fma_f32 v[222:223], v[98:99], v[152:153], v[222:223]
	v_pk_fma_f32 v[224:225], v[96:97], v[152:153], v[224:225]
	v_pk_fma_f32 v[226:227], v[94:95], v[152:153], v[226:227]
	v_pk_fma_f32 v[228:229], v[90:91], v[152:153], v[228:229]
	v_pk_fma_f32 v[230:231], v[88:89], v[152:153], v[230:231]
	s_waitcnt lgkmcnt(3)
	v_lshlrev_b32_e32 v154, 16, v142
	v_and_b32_e32 v155, 0xffff0000, v142
	v_pk_fma_f32 v[232:233], v[82:83], v[152:153], v[232:233]
	v_pk_fma_f32 v[234:235], v[74:75], v[152:153], v[234:235]
	v_pk_fma_f32 v[236:237], v[86:87], v[152:153], v[236:237]
	v_pk_fma_f32 v[238:239], v[72:73], v[152:153], v[238:239]
	v_pk_fma_f32 v[224:225], v[98:99], v[154:155], v[224:225]
	v_pk_fma_f32 v[226:227], v[96:97], v[154:155], v[226:227]
	v_pk_fma_f32 v[228:229], v[94:95], v[154:155], v[228:229]
	v_pk_fma_f32 v[230:231], v[90:91], v[154:155], v[230:231]
	v_lshlrev_b32_e32 v150, 16, v143
	v_and_b32_e32 v151, 0xffff0000, v143
	v_pk_fma_f32 v[232:233], v[88:89], v[154:155], v[232:233]
	v_pk_fma_f32 v[234:235], v[82:83], v[154:155], v[234:235]
	v_pk_fma_f32 v[236:237], v[74:75], v[154:155], v[236:237]
	v_pk_fma_f32 v[238:239], v[86:87], v[154:155], v[238:239]
	v_pk_fma_f32 v[226:227], v[98:99], v[150:151], v[226:227]
	v_pk_fma_f32 v[228:229], v[96:97], v[150:151], v[228:229]
	v_pk_fma_f32 v[230:231], v[94:95], v[150:151], v[230:231]
	v_pk_fma_f32 v[232:233], v[90:91], v[150:151], v[232:233]
	s_waitcnt lgkmcnt(2)
	v_lshlrev_b32_e32 v152, 16, v144
	v_and_b32_e32 v153, 0xffff0000, v144
	v_pk_fma_f32 v[234:235], v[88:89], v[150:151], v[234:235]
	v_pk_fma_f32 v[236:237], v[82:83], v[150:151], v[236:237]
	v_pk_fma_f32 v[238:239], v[74:75], v[150:151], v[238:239]
	v_pk_fma_f32 v[228:229], v[98:99], v[152:153], v[228:229]
	v_pk_fma_f32 v[230:231], v[96:97], v[152:153], v[230:231]
	v_pk_fma_f32 v[232:233], v[94:95], v[152:153], v[232:233]
	v_lshlrev_b32_e32 v154, 16, v145
	v_and_b32_e32 v155, 0xffff0000, v145
	v_pk_fma_f32 v[234:235], v[90:91], v[152:153], v[234:235]
	v_pk_fma_f32 v[236:237], v[88:89], v[152:153], v[236:237]
	v_pk_fma_f32 v[238:239], v[82:83], v[152:153], v[238:239]
	v_pk_fma_f32 v[230:231], v[98:99], v[154:155], v[230:231]
	v_pk_fma_f32 v[232:233], v[96:97], v[154:155], v[232:233]
	v_pk_fma_f32 v[234:235], v[94:95], v[154:155], v[234:235]
	s_waitcnt lgkmcnt(1)
	v_lshlrev_b32_e32 v150, 16, v146
	v_and_b32_e32 v151, 0xffff0000, v146
	v_pk_fma_f32 v[236:237], v[90:91], v[154:155], v[236:237]
	v_pk_fma_f32 v[238:239], v[88:89], v[154:155], v[238:239]
	v_pk_fma_f32 v[232:233], v[98:99], v[150:151], v[232:233]
	v_pk_fma_f32 v[234:235], v[96:97], v[150:151], v[234:235]
	v_lshlrev_b32_e32 v152, 16, v147
	v_and_b32_e32 v153, 0xffff0000, v147
	v_pk_fma_f32 v[236:237], v[94:95], v[150:151], v[236:237]
	v_pk_fma_f32 v[238:239], v[90:91], v[150:151], v[238:239]
	v_pk_fma_f32 v[234:235], v[98:99], v[152:153], v[234:235]
	v_pk_fma_f32 v[236:237], v[96:97], v[152:153], v[236:237]
	s_waitcnt lgkmcnt(0)
	v_lshlrev_b32_e32 v154, 16, v148
	v_and_b32_e32 v155, 0xffff0000, v148
	v_pk_fma_f32 v[238:239], v[94:95], v[152:153], v[238:239]
	v_pk_fma_f32 v[236:237], v[98:99], v[154:155], v[236:237]
	v_lshlrev_b32_e32 v150, 16, v149
	v_and_b32_e32 v151, 0xffff0000, v149
	v_pk_fma_f32 v[238:239], v[96:97], v[154:155], v[238:239]
	v_pk_fma_f32 v[238:239], v[98:99], v[150:151], v[238:239]
	ds_write_b64 v204, v[208:209] offset:0
	ds_write_b64 v204, v[210:211] offset:2048
	ds_write_b64 v204, v[212:213] offset:4096
	ds_write_b64 v204, v[214:215] offset:6144
	ds_write_b64 v204, v[216:217] offset:8192
	ds_write_b64 v204, v[218:219] offset:10240
	ds_write_b64 v204, v[220:221] offset:12288
	ds_write_b64 v204, v[222:223] offset:14336
	ds_write_b64 v204, v[224:225] offset:16384
	ds_write_b64 v204, v[226:227] offset:18432
	ds_write_b64 v204, v[228:229] offset:20480
	ds_write_b64 v204, v[230:231] offset:22528
	ds_write_b64 v204, v[232:233] offset:24576
	ds_write_b64 v204, v[234:235] offset:26624
	ds_write_b64 v204, v[236:237] offset:28672
	ds_write_b64 v204, v[238:239] offset:30720
	v_pk_mul_f32 v[104:105], v[208:209], v[208:209]
	v_pk_mul_f32 v[106:107], v[210:211], v[210:211]
	v_pk_mul_f32 v[108:109], v[212:213], v[212:213]
	v_pk_mul_f32 v[110:111], v[214:215], v[214:215]
	v_pk_mul_f32 v[112:113], v[216:217], v[216:217]
	v_pk_mul_f32 v[114:115], v[218:219], v[218:219]
	v_pk_mul_f32 v[116:117], v[220:221], v[220:221]
	v_pk_mul_f32 v[118:119], v[222:223], v[222:223]
	v_pk_mul_f32 v[120:121], v[224:225], v[224:225]
	v_pk_mul_f32 v[122:123], v[226:227], v[226:227]
	v_pk_mul_f32 v[124:125], v[228:229], v[228:229]
	v_pk_mul_f32 v[126:127], v[230:231], v[230:231]
	v_pk_mul_f32 v[128:129], v[232:233], v[232:233]
	v_pk_mul_f32 v[130:131], v[234:235], v[234:235]
	v_pk_mul_f32 v[132:133], v[236:237], v[236:237]
	v_pk_mul_f32 v[134:135], v[238:239], v[238:239]
	v_add_f32_e32 v104, v104, v105
	v_add_f32_e32 v106, v106, v107
	v_add_f32_e32 v108, v108, v109
	v_add_f32_e32 v110, v110, v111
	v_add_f32_e32 v112, v112, v113
	v_add_f32_e32 v114, v114, v115
	v_add_f32_e32 v116, v116, v117
	v_add_f32_e32 v118, v118, v119
	v_add_f32_e32 v120, v120, v121
	v_add_f32_e32 v122, v122, v123
	v_add_f32_e32 v124, v124, v125
	v_add_f32_e32 v126, v126, v127
	v_add_f32_e32 v128, v128, v129
	v_add_f32_e32 v130, v130, v131
	v_add_f32_e32 v132, v132, v133
	v_add_f32_e32 v134, v134, v135
	v_add_f32_dpp v104, v104, v104 quad_perm:[1,0,3,2] row_mask:0xf bank_mask:0xf
	v_add_f32_dpp v106, v106, v106 quad_perm:[1,0,3,2] row_mask:0xf bank_mask:0xf
	v_add_f32_dpp v108, v108, v108 quad_perm:[1,0,3,2] row_mask:0xf bank_mask:0xf
	v_add_f32_dpp v110, v110, v110 quad_perm:[1,0,3,2] row_mask:0xf bank_mask:0xf
	v_add_f32_dpp v112, v112, v112 quad_perm:[1,0,3,2] row_mask:0xf bank_mask:0xf
	v_add_f32_dpp v114, v114, v114 quad_perm:[1,0,3,2] row_mask:0xf bank_mask:0xf
	v_add_f32_dpp v116, v116, v116 quad_perm:[1,0,3,2] row_mask:0xf bank_mask:0xf
	v_add_f32_dpp v118, v118, v118 quad_perm:[1,0,3,2] row_mask:0xf bank_mask:0xf
	v_add_f32_dpp v120, v120, v120 quad_perm:[1,0,3,2] row_mask:0xf bank_mask:0xf
	v_add_f32_dpp v122, v122, v122 quad_perm:[1,0,3,2] row_mask:0xf bank_mask:0xf
	v_add_f32_dpp v124, v124, v124 quad_perm:[1,0,3,2] row_mask:0xf bank_mask:0xf
	v_add_f32_dpp v126, v126, v126 quad_perm:[1,0,3,2] row_mask:0xf bank_mask:0xf
	v_add_f32_dpp v128, v128, v128 quad_perm:[1,0,3,2] row_mask:0xf bank_mask:0xf
	v_add_f32_dpp v130, v130, v130 quad_perm:[1,0,3,2] row_mask:0xf bank_mask:0xf
	v_add_f32_dpp v132, v132, v132 quad_perm:[1,0,3,2] row_mask:0xf bank_mask:0xf
	v_add_f32_dpp v134, v134, v134 quad_perm:[1,0,3,2] row_mask:0xf bank_mask:0xf
	v_add_f32_dpp v104, v104, v104 quad_perm:[2,3,0,1] row_mask:0xf bank_mask:0xf
	v_add_f32_dpp v106, v106, v106 quad_perm:[2,3,0,1] row_mask:0xf bank_mask:0xf
	v_add_f32_dpp v108, v108, v108 quad_perm:[2,3,0,1] row_mask:0xf bank_mask:0xf
	v_add_f32_dpp v110, v110, v110 quad_perm:[2,3,0,1] row_mask:0xf bank_mask:0xf
	v_add_f32_dpp v112, v112, v112 quad_perm:[2,3,0,1] row_mask:0xf bank_mask:0xf
	v_add_f32_dpp v114, v114, v114 quad_perm:[2,3,0,1] row_mask:0xf bank_mask:0xf
	v_add_f32_dpp v116, v116, v116 quad_perm:[2,3,0,1] row_mask:0xf bank_mask:0xf
	v_add_f32_dpp v118, v118, v118 quad_perm:[2,3,0,1] row_mask:0xf bank_mask:0xf
	v_add_f32_dpp v120, v120, v120 quad_perm:[2,3,0,1] row_mask:0xf bank_mask:0xf
	v_add_f32_dpp v122, v122, v122 quad_perm:[2,3,0,1] row_mask:0xf bank_mask:0xf
	v_add_f32_dpp v124, v124, v124 quad_perm:[2,3,0,1] row_mask:0xf bank_mask:0xf
	v_add_f32_dpp v126, v126, v126 quad_perm:[2,3,0,1] row_mask:0xf bank_mask:0xf
	v_add_f32_dpp v128, v128, v128 quad_perm:[2,3,0,1] row_mask:0xf bank_mask:0xf
	v_add_f32_dpp v130, v130, v130 quad_perm:[2,3,0,1] row_mask:0xf bank_mask:0xf
	v_add_f32_dpp v132, v132, v132 quad_perm:[2,3,0,1] row_mask:0xf bank_mask:0xf
	v_add_f32_dpp v134, v134, v134 quad_perm:[2,3,0,1] row_mask:0xf bank_mask:0xf
	v_add_f32_dpp v104, v104, v104 row_ror:4 row_mask:0xf bank_mask:0xf
	v_add_f32_dpp v106, v106, v106 row_ror:4 row_mask:0xf bank_mask:0xf
	v_add_f32_dpp v108, v108, v108 row_ror:4 row_mask:0xf bank_mask:0xf
	v_add_f32_dpp v110, v110, v110 row_ror:4 row_mask:0xf bank_mask:0xf
	v_add_f32_dpp v112, v112, v112 row_ror:4 row_mask:0xf bank_mask:0xf
	v_add_f32_dpp v114, v114, v114 row_ror:4 row_mask:0xf bank_mask:0xf
	v_add_f32_dpp v116, v116, v116 row_ror:4 row_mask:0xf bank_mask:0xf
	v_add_f32_dpp v118, v118, v118 row_ror:4 row_mask:0xf bank_mask:0xf
	v_add_f32_dpp v120, v120, v120 row_ror:4 row_mask:0xf bank_mask:0xf
	v_add_f32_dpp v122, v122, v122 row_ror:4 row_mask:0xf bank_mask:0xf
	v_add_f32_dpp v124, v124, v124 row_ror:4 row_mask:0xf bank_mask:0xf
	v_add_f32_dpp v126, v126, v126 row_ror:4 row_mask:0xf bank_mask:0xf
	v_add_f32_dpp v128, v128, v128 row_ror:4 row_mask:0xf bank_mask:0xf
	v_add_f32_dpp v130, v130, v130 row_ror:4 row_mask:0xf bank_mask:0xf
	v_add_f32_dpp v132, v132, v132 row_ror:4 row_mask:0xf bank_mask:0xf
	v_add_f32_dpp v134, v134, v134 row_ror:4 row_mask:0xf bank_mask:0xf
	v_add_f32_dpp v104, v104, v104 row_ror:8 row_mask:0xf bank_mask:0xf
	v_add_f32_dpp v106, v106, v106 row_ror:8 row_mask:0xf bank_mask:0xf
	v_add_f32_dpp v108, v108, v108 row_ror:8 row_mask:0xf bank_mask:0xf
	v_add_f32_dpp v110, v110, v110 row_ror:8 row_mask:0xf bank_mask:0xf
	v_add_f32_dpp v112, v112, v112 row_ror:8 row_mask:0xf bank_mask:0xf
	v_add_f32_dpp v114, v114, v114 row_ror:8 row_mask:0xf bank_mask:0xf
	v_add_f32_dpp v116, v116, v116 row_ror:8 row_mask:0xf bank_mask:0xf
	v_add_f32_dpp v118, v118, v118 row_ror:8 row_mask:0xf bank_mask:0xf
	v_add_f32_dpp v120, v120, v120 row_ror:8 row_mask:0xf bank_mask:0xf
	v_add_f32_dpp v122, v122, v122 row_ror:8 row_mask:0xf bank_mask:0xf
	v_add_f32_dpp v124, v124, v124 row_ror:8 row_mask:0xf bank_mask:0xf
	v_add_f32_dpp v126, v126, v126 row_ror:8 row_mask:0xf bank_mask:0xf
	v_add_f32_dpp v128, v128, v128 row_ror:8 row_mask:0xf bank_mask:0xf
	v_add_f32_dpp v130, v130, v130 row_ror:8 row_mask:0xf bank_mask:0xf
	v_add_f32_dpp v132, v132, v132 row_ror:8 row_mask:0xf bank_mask:0xf
	v_add_f32_dpp v134, v134, v134 row_ror:8 row_mask:0xf bank_mask:0xf
	v_add_f32_dpp v104, v104, v104 row_bcast:15 row_mask:0xa bank_mask:0xf
	v_add_f32_dpp v106, v106, v106 row_bcast:15 row_mask:0xa bank_mask:0xf
	v_add_f32_dpp v108, v108, v108 row_bcast:15 row_mask:0xa bank_mask:0xf
	v_add_f32_dpp v110, v110, v110 row_bcast:15 row_mask:0xa bank_mask:0xf
	v_add_f32_dpp v112, v112, v112 row_bcast:15 row_mask:0xa bank_mask:0xf
	v_add_f32_dpp v114, v114, v114 row_bcast:15 row_mask:0xa bank_mask:0xf
	v_add_f32_dpp v116, v116, v116 row_bcast:15 row_mask:0xa bank_mask:0xf
	v_add_f32_dpp v118, v118, v118 row_bcast:15 row_mask:0xa bank_mask:0xf
	v_add_f32_dpp v120, v120, v120 row_bcast:15 row_mask:0xa bank_mask:0xf
	v_add_f32_dpp v122, v122, v122 row_bcast:15 row_mask:0xa bank_mask:0xf
	v_add_f32_dpp v124, v124, v124 row_bcast:15 row_mask:0xa bank_mask:0xf
	v_add_f32_dpp v126, v126, v126 row_bcast:15 row_mask:0xa bank_mask:0xf
	v_add_f32_dpp v128, v128, v128 row_bcast:15 row_mask:0xa bank_mask:0xf
	v_add_f32_dpp v130, v130, v130 row_bcast:15 row_mask:0xa bank_mask:0xf
	v_add_f32_dpp v132, v132, v132 row_bcast:15 row_mask:0xa bank_mask:0xf
	v_add_f32_dpp v134, v134, v134 row_bcast:15 row_mask:0xa bank_mask:0xf
	v_add_f32_dpp v104, v104, v104 row_bcast:31 row_mask:0xc bank_mask:0xf
	v_add_f32_dpp v106, v106, v106 row_bcast:31 row_mask:0xc bank_mask:0xf
	v_add_f32_dpp v108, v108, v108 row_bcast:31 row_mask:0xc bank_mask:0xf
	v_add_f32_dpp v110, v110, v110 row_bcast:31 row_mask:0xc bank_mask:0xf
	v_add_f32_dpp v112, v112, v112 row_bcast:31 row_mask:0xc bank_mask:0xf
	v_add_f32_dpp v114, v114, v114 row_bcast:31 row_mask:0xc bank_mask:0xf
	v_add_f32_dpp v116, v116, v116 row_bcast:31 row_mask:0xc bank_mask:0xf
	v_add_f32_dpp v118, v118, v118 row_bcast:31 row_mask:0xc bank_mask:0xf
	v_add_f32_dpp v120, v120, v120 row_bcast:31 row_mask:0xc bank_mask:0xf
	v_add_f32_dpp v122, v122, v122 row_bcast:31 row_mask:0xc bank_mask:0xf
	v_add_f32_dpp v124, v124, v124 row_bcast:31 row_mask:0xc bank_mask:0xf
	v_add_f32_dpp v126, v126, v126 row_bcast:31 row_mask:0xc bank_mask:0xf
	v_add_f32_dpp v128, v128, v128 row_bcast:31 row_mask:0xc bank_mask:0xf
	v_add_f32_dpp v130, v130, v130 row_bcast:31 row_mask:0xc bank_mask:0xf
	v_add_f32_dpp v132, v132, v132 row_bcast:31 row_mask:0xc bank_mask:0xf
	v_add_f32_dpp v134, v134, v134 row_bcast:31 row_mask:0xc bank_mask:0xf
	s_mov_b64 s[48:49], exec
	s_mov_b32 s18, 0
	s_brev_b32 s19, 1
	s_mov_b64 exec, s[18:19]
	ds_write_b32 v205, v104 offset:0
	ds_write_b32 v205, v106 offset:16
	ds_write_b32 v205, v108 offset:32
	ds_write_b32 v205, v110 offset:48
	ds_write_b32 v205, v112 offset:64
	ds_write_b32 v205, v114 offset:80
	ds_write_b32 v205, v116 offset:96
	ds_write_b32 v205, v118 offset:112
	ds_write_b32 v205, v120 offset:128
	ds_write_b32 v205, v122 offset:144
	ds_write_b32 v205, v124 offset:160
	ds_write_b32 v205, v126 offset:176
	ds_write_b32 v205, v128 offset:192
	ds_write_b32 v205, v130 offset:208
	ds_write_b32 v205, v132 offset:224
	ds_write_b32 v205, v134 offset:240
	s_mov_b64 exec, s[48:49]
